# E3 sample-row tiles: residual loads hoisted too (on top of O3 wide hoist)
# baseline (speedup 1.0000x reference)
;   const int tid = otid(), lane = tid & 63, w = tid >> 6, r = lane & 31, h = lane >> 5;
;   const int wm = w >> 1, wn = w & 1;
;   constexpr int IM = BM / 64;
;   constexpr int NA = BM / 32;
;   f32x16 acc[IM][2];
; #pragma unroll
;   for (int i = 0; i < IM; ++i)
; #pragma unroll
;     for (int j = 0; j < 2; ++j)
; #pragma unroll
;       for (int e = 0; e < 16; ++e) acc[i][j][e] = 0.f;
;   constexpr int NK = K / 64;
;   constexpr int OPB = 128 * 128;
;   constexpr int BUFB = 2 * OPB;
;   const int lrow = tid >> 3, cpos = tid & 7;
;   const u16* ap[4]; const u16* bp[4];
; #pragma unroll
;   for (int i = 0; i < 4; ++i) {
;     const int row = lrow + 32 * i;
;     const int sc = cpos ^ ((row >> 1) & 7);
;     ap[i] = A + (size_t)(m0 + (i < NA ? row : 0)) * lda + sc * 8;
;     bp[i] = Bt + (size_t)(n0 + row) * ldb + sc * 8;
;   }
;   char* const ldst = smem + tid * 16;
;   __syncthreads();
; #pragma unroll
;   for (int i = 0; i < 4; ++i) {
;     if (i < NA) __builtin_amdgcn_global_load_lds((const unsigned*)(ap[i]), (unsigned*)(ldst + i * 4096), 16, 0, 0);
;     __builtin_amdgcn_global_load_lds((const unsigned*)(bp[i]), (unsigned*)(ldst + OPB + i * 4096), 16, 0, 0);
;   }
;   int aoff[2], boff[2], aswz[2], bswz[2];
; #pragma unroll
;   for (int i = 0; i < 2; ++i) {
;     const int ra_ = wm * (BM / 2) + (i < IM ? i : 0) * 32 + r, rb_ = wn * 64 + i * 32 + r;
;     aoff[i] = ra_ * 128; aswz[i] = (ra_ >> 1) & 7;
;     boff[i] = rb_ * 128; bswz[i] = (rb_ >> 1) & 7;
;   }
;   for (int kt = 0; kt < NK; ++kt) {
;     asm volatile("s_waitcnt vmcnt(0)" ::: "memory");
;     __syncthreads();
;     const int cur = (kt & 1) * BUFB, nxt = BUFB - cur;
;     if (kt + 1 < NK) {
; #pragma unroll
;       for (int i = 0; i < 4; ++i) {
;         if (i < NA) __builtin_amdgcn_global_load_lds((const unsigned*)(ap[i] + (kt + 1) * 64), (unsigned*)(ldst + nxt + i * 4096), 16, 0, 0);
;         __builtin_amdgcn_global_load_lds((const unsigned*)(bp[i] + (kt + 1) * 64), (unsigned*)(ldst + nxt + OPB + i * 4096), 16, 0, 0);
;       }
;     }
;     const char* As = smem + cur; const char* Bs = smem + cur + OPB;
; __global__ void __launch_bounds__(256, 2) fwd_megakernel(Params p) {
;     ...
;   for (TileSched ts = tile_sched(64); ts.t < ts.hi; ts.t += ts.step) {
;     const int hm = ts.t >> 3, nt = ts.t & 7;
;     gemm_tile<1024, 64>(p.A2(), 1024, p.Wt_out_e(), 1024, TP + hm * 64, nt * 128, smem);
.LBB0_780:
	s_add_i32 s37, s37, s33
	s_add_i32 s43, s43, s44
	s_add_i32 s45, s45, s46
	s_cmp_ge_i32 s37, s42
	s_cbranch_scc1 .LBB0_813
.LBB0_781:
	v_mov_b32_e32 v6, v186
	s_and_b32 s40, s43, 0xffffffc0
	s_addk_i32 s40, 0x4000
	v_lshrrev_b32_e32 v0, 4, v6
	v_ashrrev_i32_e32 v7, 3, v6
	v_xor_b32_e32 v0, v0, v6
	v_lshlrev_b32_e32 v0, 4, v0
	v_add_u32_e32 v4, s40, v7
	v_and_b32_e32 v32, 0x70, v0
	v_ashrrev_i32_e32 v5, 31, v4
	s_and_b32 s49, s45, 0x380
	v_lshl_add_u64 v[0:1], s[38:39], 0, v[32:33]
	v_lshlrev_b64 v[4:5], 11, v[4:5]
	v_lshl_add_u64 v[36:37], v[0:1], 0, v[4:5]
	v_add_u32_e32 v4, s49, v7
	v_ashrrev_i32_e32 v5, 31, v4
	v_lshl_add_u64 v[2:3], s[0:1], 0, v[32:33]
	v_lshlrev_b64 v[4:5], 11, v[4:5]
	v_add_u32_e32 v7, 32, v7
	v_lshl_add_u64 v[34:35], v[2:3], 0, v[4:5]
	v_add_u32_e32 v4, s40, v7
	v_ashrrev_i32_e32 v5, 31, v4
	v_lshlrev_b32_e32 v59, 4, v6
	v_lshlrev_b64 v[4:5], 11, v[4:5]
	v_add_u32_e32 v60, 0x4000, v59
	v_readfirstlane_b32 s70, v59
	v_lshl_add_u64 v[38:39], v[0:1], 0, v[4:5]
	v_add_u32_e32 v0, s49, v7
	s_mov_b32 m0, s70
	v_readfirstlane_b32 s61, v60
	v_add_u32_e32 v63, 0x1000, v59
	v_ashrrev_i32_e32 v1, 31, v0
	s_barrier
	global_load_lds_dwordx4 v[36:37], off
	s_mov_b32 m0, s61
	v_readfirstlane_b32 s62, v63
	v_add_u32_e32 v64, 0x5000, v59
	v_lshlrev_b64 v[0:1], 11, v[0:1]
	global_load_lds_dwordx4 v[34:35], off
	s_mov_b32 m0, s62
	v_readfirstlane_b32 s69, v64
	v_add_u32_e32 v62, 0x6000, v59
	v_lshl_add_u64 v[40:41], v[2:3], 0, v[0:1]
	s_mov_b64 s[56:57], 0x20000
	global_load_lds_dwordx4 v[38:39], off
	s_mov_b32 m0, s69
	v_readfirstlane_b32 s68, v62
	v_add_u32_e32 v61, 0x7000, v59
	v_lshl_add_u64 v[0:1], v[34:35], 0, s[56:57]
	s_mov_b64 s[56:57], 0x30000
	global_load_lds_dwordx4 v[40:41], off
	s_mov_b32 m0, s68
	v_readfirstlane_b32 s63, v61
	v_add_u32_e32 v54, 0x8000, v59
	v_lshl_add_u64 v[2:3], v[34:35], 0, s[56:57]
	global_load_lds_dwordx4 v[0:1], off
	s_mov_b32 m0, s63
	v_add_u32_e32 v53, 0xc000, v59
	v_readfirstlane_b32 s58, v54
	global_load_lds_dwordx4 v[2:3], off
	v_lshl_add_u64 v[0:1], v[36:37], 0, s[4:5]
	s_mov_b32 m0, s58
	v_readfirstlane_b32 s41, v53
	v_add_u32_e32 v55, 0x9000, v59
	s_waitcnt vmcnt(0)
	s_waitcnt vmcnt(0) lgkmcnt(0)
	s_barrier
	global_load_lds_dwordx4 v[0:1], off
	v_lshl_add_u64 v[0:1], v[34:35], 0, s[4:5]
	s_mov_b32 m0, s41
	v_readfirstlane_b32 s56, v55
	v_add_u32_e32 v56, 0xd000, v59
	global_load_lds_dwordx4 v[0:1], off
	v_lshl_add_u64 v[0:1], v[38:39], 0, s[4:5]
	s_mov_b32 m0, s56
	v_readfirstlane_b32 s57, v56
	v_add_u32_e32 v57, 0xe000, v59
	global_load_lds_dwordx4 v[0:1], off
	v_lshl_add_u64 v[0:1], v[40:41], 0, s[4:5]
	s_mov_b32 m0, s57
	s_mov_b64 s[72:73], 0x20080
	v_readfirstlane_b32 s59, v57
	v_add_u32_e32 v58, 0xf000, v59
	global_load_lds_dwordx4 v[0:1], off
	v_lshl_add_u64 v[0:1], v[34:35], 0, s[72:73]
	s_mov_b32 m0, s59
	s_mov_b64 s[72:73], 0x30080
	v_readfirstlane_b32 s60, v58
	global_load_lds_dwordx4 v[0:1], off
	v_lshl_add_u64 v[0:1], v[34:35], 0, s[72:73]
	s_mov_b32 m0, s60
	v_and_b32_e32 v32, 31, v6
	global_load_lds_dwordx4 v[0:1], off
	v_ashrrev_i32_e32 v42, 7, v6
	v_bfe_u32 v43, v6, 5, 1
	v_bfe_u32 v44, v6, 6, 1
	v_lshlrev_b32_e32 v0, 7, v32
	v_lshrrev_b32_e32 v1, 1, v6
	v_bfe_u32 v2, v6, 1, 3
	v_lshl_or_b32 v4, v42, 12, v0
	v_lshl_or_b32 v5, v44, 13, v0
	v_bitop3_b32 v0, v1, v43, 7 bitop3:0x6c
	v_bitop3_b32 v1, v43, v2, 2 bitop3:0x36
	v_lshlrev_b32_e32 v6, 4, v1
	v_bitop3_b32 v1, v43, v2, 4 bitop3:0x36
	v_lshlrev_b32_e32 v7, 4, v1
	v_bitop3_b32 v1, v43, v2, 6 bitop3:0x36
	v_lshlrev_b32_e32 v0, 4, v0
	v_lshlrev_b32_e32 v8, 4, v1
	v_or_b32_e32 v45, v4, v0
	v_or_b32_e32 v46, v5, v0
	v_or_b32_e32 v48, v5, v6
	v_or_b32_e32 v49, v4, v7
	v_or_b32_e32 v50, v5, v7
	v_or_b32_e32 v52, v5, v8
	ds_read_b128 v[16:19], v45
	ds_read_b128 v[0:3], v46 offset:16384
	v_or_b32_e32 v47, v4, v6
	ds_read_b128 v[20:23], v46 offset:20480
	ds_read_b128 v[66:69], v47
	ds_read_b128 v[70:73], v48 offset:16384
	ds_read_b128 v[74:77], v48 offset:20480
	ds_read_b128 v[78:81], v49
	ds_read_b128 v[82:85], v50 offset:16384
	v_or_b32_e32 v51, v4, v8
	ds_read_b128 v[86:89], v50 offset:20480
	ds_read_b128 v[90:93], v51
	ds_read_b128 v[94:97], v52 offset:16384
	ds_read_b128 v[98:101], v52 offset:20480
	s_setprio 1
	s_waitcnt lgkmcnt(0)
	v_mfma_f32_32x32x16_bf16 v[0:15], v[16:19], v[0:3], 0
	v_mfma_f32_32x32x16_bf16 v[16:31], v[16:19], v[20:23], 0
	v_mfma_f32_32x32x16_bf16 v[0:15], v[66:69], v[70:73], v[0:15]
	v_mfma_f32_32x32x16_bf16 v[16:31], v[66:69], v[74:77], v[16:31]
	v_mfma_f32_32x32x16_bf16 v[0:15], v[78:81], v[82:85], v[0:15]
	v_mfma_f32_32x32x16_bf16 v[16:31], v[78:81], v[86:89], v[16:31]
	v_mfma_f32_32x32x16_bf16 v[0:15], v[90:93], v[94:97], v[0:15]
	v_mfma_f32_32x32x16_bf16 v[16:31], v[90:93], v[98:101], v[16:31]
	s_setprio 0
	s_mov_b32 m0, s70
	v_lshl_add_u64 v[66:67], v[36:37], 0, s[6:7]
	s_waitcnt vmcnt(0)
	s_waitcnt vmcnt(0)
	s_barrier
; #define MFMA(a, b, c) __builtin_amdgcn_mfma_f32_32x32x16_bf16((a), (b), (c), 0, 0, 0)
;     ...
;   for (int kt = 0; kt < NK; ++kt) {
;     asm volatile("s_waitcnt vmcnt(0)" ::: "memory");
;     __syncthreads();
;     const int cur = (kt & 1) * BUFB, nxt = BUFB - cur;
;     if (kt + 1 < NK) {
; #pragma unroll
;       for (int i = 0; i < 4; ++i) {
;         if (i < NA) __builtin_amdgcn_global_load_lds((const unsigned*)(ap[i] + (kt + 1) * 64), (unsigned*)(ldst + nxt + i * 4096), 16, 0, 0);
;         __builtin_amdgcn_global_load_lds((const unsigned*)(bp[i] + (kt + 1) * 64), (unsigned*)(ldst + nxt + OPB + i * 4096), 16, 0, 0);
;       }
;     }
;     const char* As = smem + cur; const char* Bs = smem + cur + OPB;
;     bf16x8 a[4][IM], b[4][2];
; #pragma unroll
;     for (int kk = 0; kk < 4; ++kk)
; #pragma unroll
;       for (int i = 0; i < 2; ++i) {
;         if (i < IM) a[kk][i] = *(const bf16x8*)(As + aoff[i] + (((2 * kk + h) ^ aswz[i]) << 4));
;         b[kk][i] = *(const bf16x8*)(Bs + boff[i] + (((2 * kk + h) ^ bswz[i]) << 4));
;       }
;     __builtin_amdgcn_sched_barrier(0);
;     __builtin_amdgcn_s_setprio(1);
; #pragma unroll
;     for (int kk = 0; kk < 4; ++kk)
; #pragma unroll
;       for (int i = 0; i < IM; ++i)
; #pragma unroll
;         for (int j = 0; j < 2; ++j) acc[i][j] = MFMA(a[kk][i], b[kk][j], acc[i][j]);
;     __builtin_amdgcn_s_setprio(0);
;   }
	global_load_lds_dwordx4 v[66:67], off
	v_lshl_add_u64 v[66:67], v[34:35], 0, s[6:7]
	s_mov_b32 m0, s61
	s_mov_b64 s[72:73], 0x20100
	global_load_lds_dwordx4 v[66:67], off
	v_lshl_add_u64 v[66:67], v[38:39], 0, s[6:7]
	s_mov_b32 m0, s62
	s_nop 0
	global_load_lds_dwordx4 v[66:67], off
	v_lshl_add_u64 v[66:67], v[40:41], 0, s[6:7]
	s_mov_b32 m0, s69
	s_nop 0
	global_load_lds_dwordx4 v[66:67], off
	v_lshl_add_u64 v[66:67], v[34:35], 0, s[72:73]
	s_mov_b32 m0, s68
	s_mov_b64 s[72:73], 0x30100
	global_load_lds_dwordx4 v[66:67], off
	v_lshl_add_u64 v[66:67], v[34:35], 0, s[72:73]
	s_mov_b32 m0, s63
	s_nop 0
	global_load_lds_dwordx4 v[66:67], off
	ds_read_b128 v[66:69], v45 offset:32768
	ds_read_b128 v[70:73], v46 offset:49152
	ds_read_b128 v[74:77], v46 offset:53248
	ds_read_b128 v[78:81], v47 offset:32768
	ds_read_b128 v[82:85], v48 offset:49152
	ds_read_b128 v[86:89], v48 offset:53248
	ds_read_b128 v[90:93], v49 offset:32768
	ds_read_b128 v[94:97], v50 offset:49152
	ds_read_b128 v[98:101], v50 offset:53248
	ds_read_b128 v[102:105], v51 offset:32768
	ds_read_b128 v[106:109], v52 offset:49152
	ds_read_b128 v[110:113], v52 offset:53248
	s_setprio 1
	s_waitcnt lgkmcnt(0)
	v_mfma_f32_32x32x16_bf16 v[0:15], v[66:69], v[70:73], v[0:15]
	v_mfma_f32_32x32x16_bf16 v[16:31], v[66:69], v[74:77], v[16:31]
	v_mfma_f32_32x32x16_bf16 v[0:15], v[78:81], v[82:85], v[0:15]
	v_mfma_f32_32x32x16_bf16 v[16:31], v[78:81], v[86:89], v[16:31]
	v_mfma_f32_32x32x16_bf16 v[0:15], v[90:93], v[94:97], v[0:15]
	v_mfma_f32_32x32x16_bf16 v[16:31], v[90:93], v[98:101], v[16:31]
	v_mfma_f32_32x32x16_bf16 v[0:15], v[102:105], v[106:109], v[0:15]
	v_mfma_f32_32x32x16_bf16 v[16:31], v[102:105], v[110:113], v[16:31]
	s_setprio 0
	s_mov_b32 m0, s58
	v_lshl_add_u64 v[66:67], v[36:37], 0, s[8:9]
	s_waitcnt vmcnt(0)
	s_waitcnt vmcnt(0)
	s_barrier
	global_load_lds_dwordx4 v[66:67], off
	v_lshl_add_u64 v[66:67], v[34:35], 0, s[8:9]
	s_mov_b32 m0, s41
	s_mov_b64 s[72:73], 0x20180
	global_load_lds_dwordx4 v[66:67], off
	v_lshl_add_u64 v[66:67], v[38:39], 0, s[8:9]
	s_mov_b32 m0, s56
	s_nop 0
	global_load_lds_dwordx4 v[66:67], off
	v_lshl_add_u64 v[66:67], v[40:41], 0, s[8:9]
	s_mov_b32 m0, s57
	s_nop 0
	global_load_lds_dwordx4 v[66:67], off
	v_lshl_add_u64 v[66:67], v[34:35], 0, s[72:73]
	s_mov_b32 m0, s59
	s_mov_b64 s[72:73], 0x30180
	global_load_lds_dwordx4 v[66:67], off
	v_lshl_add_u64 v[66:67], v[34:35], 0, s[72:73]
	s_mov_b32 m0, s60
	s_nop 0
	global_load_lds_dwordx4 v[66:67], off
	ds_read_b128 v[66:69], v45
	ds_read_b128 v[70:73], v46 offset:16384
	ds_read_b128 v[74:77], v46 offset:20480
	ds_read_b128 v[78:81], v47
	ds_read_b128 v[82:85], v48 offset:16384
	ds_read_b128 v[86:89], v48 offset:20480
	ds_read_b128 v[90:93], v49
	ds_read_b128 v[94:97], v50 offset:16384
	ds_read_b128 v[98:101], v50 offset:20480
	ds_read_b128 v[102:105], v51
	ds_read_b128 v[106:109], v52 offset:16384
	ds_read_b128 v[110:113], v52 offset:20480
	s_setprio 1
	s_waitcnt lgkmcnt(0)
	v_mfma_f32_32x32x16_bf16 v[0:15], v[66:69], v[70:73], v[0:15]
	v_mfma_f32_32x32x16_bf16 v[16:31], v[66:69], v[74:77], v[16:31]
	v_mfma_f32_32x32x16_bf16 v[0:15], v[78:81], v[82:85], v[0:15]
	v_mfma_f32_32x32x16_bf16 v[16:31], v[78:81], v[86:89], v[16:31]
	v_mfma_f32_32x32x16_bf16 v[0:15], v[90:93], v[94:97], v[0:15]
	v_mfma_f32_32x32x16_bf16 v[16:31], v[90:93], v[98:101], v[16:31]
	v_mfma_f32_32x32x16_bf16 v[0:15], v[102:105], v[106:109], v[0:15]
	v_mfma_f32_32x32x16_bf16 v[16:31], v[102:105], v[110:113], v[16:31]
	s_setprio 0
	s_mov_b32 m0, s70
	v_lshl_add_u64 v[66:67], v[36:37], 0, s[10:11]
	s_waitcnt vmcnt(0)
	s_waitcnt vmcnt(0)
	s_barrier
	global_load_lds_dwordx4 v[66:67], off
	v_lshl_add_u64 v[66:67], v[34:35], 0, s[10:11]
	s_mov_b32 m0, s61
	s_mov_b64 s[72:73], 0x20200
	global_load_lds_dwordx4 v[66:67], off
	v_lshl_add_u64 v[66:67], v[38:39], 0, s[10:11]
	s_mov_b32 m0, s62
	s_nop 0
	global_load_lds_dwordx4 v[66:67], off
	v_lshl_add_u64 v[66:67], v[40:41], 0, s[10:11]
	s_mov_b32 m0, s69
	s_nop 0
	global_load_lds_dwordx4 v[66:67], off
	v_lshl_add_u64 v[66:67], v[34:35], 0, s[72:73]
	s_mov_b32 m0, s68
	s_mov_b64 s[72:73], 0x30200
	global_load_lds_dwordx4 v[66:67], off
	v_lshl_add_u64 v[66:67], v[34:35], 0, s[72:73]
	s_mov_b32 m0, s63
	s_nop 0
	global_load_lds_dwordx4 v[66:67], off
	ds_read_b128 v[66:69], v45 offset:32768
	ds_read_b128 v[70:73], v46 offset:49152
	ds_read_b128 v[74:77], v46 offset:53248
	ds_read_b128 v[78:81], v47 offset:32768
	ds_read_b128 v[82:85], v48 offset:49152
	ds_read_b128 v[86:89], v48 offset:53248
	ds_read_b128 v[90:93], v49 offset:32768
	ds_read_b128 v[94:97], v50 offset:49152
	ds_read_b128 v[98:101], v50 offset:53248
	ds_read_b128 v[102:105], v51 offset:32768
	ds_read_b128 v[106:109], v52 offset:49152
	ds_read_b128 v[110:113], v52 offset:53248
	s_setprio 1
	s_waitcnt lgkmcnt(0)
	v_mfma_f32_32x32x16_bf16 v[0:15], v[66:69], v[70:73], v[0:15]
	v_mfma_f32_32x32x16_bf16 v[16:31], v[66:69], v[74:77], v[16:31]
	v_mfma_f32_32x32x16_bf16 v[0:15], v[78:81], v[82:85], v[0:15]
	v_mfma_f32_32x32x16_bf16 v[16:31], v[78:81], v[86:89], v[16:31]
	v_mfma_f32_32x32x16_bf16 v[0:15], v[90:93], v[94:97], v[0:15]
	v_mfma_f32_32x32x16_bf16 v[16:31], v[90:93], v[98:101], v[16:31]
	v_mfma_f32_32x32x16_bf16 v[0:15], v[102:105], v[106:109], v[0:15]
	v_mfma_f32_32x32x16_bf16 v[16:31], v[102:105], v[110:113], v[16:31]
	s_setprio 0
	s_mov_b32 m0, s58
	v_lshl_add_u64 v[66:67], v[36:37], 0, s[12:13]
	s_waitcnt vmcnt(0)
	s_waitcnt vmcnt(0)
	s_barrier
; #define MFMA(a, b, c) __builtin_amdgcn_mfma_f32_32x32x16_bf16((a), (b), (c), 0, 0, 0)
;     ...
;   for (int kt = 0; kt < NK; ++kt) {
;     asm volatile("s_waitcnt vmcnt(0)" ::: "memory");
;     __syncthreads();
;     const int cur = (kt & 1) * BUFB, nxt = BUFB - cur;
;     if (kt + 1 < NK) {
; #pragma unroll
;       for (int i = 0; i < 4; ++i) {
;         if (i < NA) __builtin_amdgcn_global_load_lds((const unsigned*)(ap[i] + (kt + 1) * 64), (unsigned*)(ldst + nxt + i * 4096), 16, 0, 0);
;         __builtin_amdgcn_global_load_lds((const unsigned*)(bp[i] + (kt + 1) * 64), (unsigned*)(ldst + nxt + OPB + i * 4096), 16, 0, 0);
;       }
;     }
;     const char* As = smem + cur; const char* Bs = smem + cur + OPB;
;     bf16x8 a[4][IM], b[4][2];
; #pragma unroll
;     for (int kk = 0; kk < 4; ++kk)
; #pragma unroll
;       for (int i = 0; i < 2; ++i) {
;         if (i < IM) a[kk][i] = *(const bf16x8*)(As + aoff[i] + (((2 * kk + h) ^ aswz[i]) << 4));
;         b[kk][i] = *(const bf16x8*)(Bs + boff[i] + (((2 * kk + h) ^ bswz[i]) << 4));
;       }
;     __builtin_amdgcn_sched_barrier(0);
;     __builtin_amdgcn_s_setprio(1);
; #pragma unroll
;     for (int kk = 0; kk < 4; ++kk)
; #pragma unroll
;       for (int i = 0; i < IM; ++i)
; #pragma unroll
;         for (int j = 0; j < 2; ++j) acc[i][j] = MFMA(a[kk][i], b[kk][j], acc[i][j]);
;     __builtin_amdgcn_s_setprio(0);
;   }
	global_load_lds_dwordx4 v[66:67], off
	v_lshl_add_u64 v[66:67], v[34:35], 0, s[12:13]
	s_mov_b32 m0, s41
	s_mov_b64 s[72:73], 0x20280
	global_load_lds_dwordx4 v[66:67], off
	v_lshl_add_u64 v[66:67], v[38:39], 0, s[12:13]
	s_mov_b32 m0, s56
	s_nop 0
	global_load_lds_dwordx4 v[66:67], off
	v_lshl_add_u64 v[66:67], v[40:41], 0, s[12:13]
	s_mov_b32 m0, s57
	s_nop 0
	global_load_lds_dwordx4 v[66:67], off
	v_lshl_add_u64 v[66:67], v[34:35], 0, s[72:73]
	s_mov_b32 m0, s59
	s_mov_b64 s[72:73], 0x30280
	global_load_lds_dwordx4 v[66:67], off
	v_lshl_add_u64 v[66:67], v[34:35], 0, s[72:73]
	s_mov_b32 m0, s60
	s_nop 0
	global_load_lds_dwordx4 v[66:67], off
	ds_read_b128 v[66:69], v45
	ds_read_b128 v[70:73], v46 offset:16384
	ds_read_b128 v[74:77], v46 offset:20480
	ds_read_b128 v[78:81], v47
	ds_read_b128 v[82:85], v48 offset:16384
	ds_read_b128 v[86:89], v48 offset:20480
	ds_read_b128 v[90:93], v49
	ds_read_b128 v[94:97], v50 offset:16384
	ds_read_b128 v[98:101], v50 offset:20480
	ds_read_b128 v[102:105], v51
	ds_read_b128 v[106:109], v52 offset:16384
	ds_read_b128 v[110:113], v52 offset:20480
	s_setprio 1
	s_waitcnt lgkmcnt(0)
	v_mfma_f32_32x32x16_bf16 v[0:15], v[66:69], v[70:73], v[0:15]
	v_mfma_f32_32x32x16_bf16 v[16:31], v[66:69], v[74:77], v[16:31]
	v_mfma_f32_32x32x16_bf16 v[0:15], v[78:81], v[82:85], v[0:15]
	v_mfma_f32_32x32x16_bf16 v[16:31], v[78:81], v[86:89], v[16:31]
	v_mfma_f32_32x32x16_bf16 v[0:15], v[90:93], v[94:97], v[0:15]
	v_mfma_f32_32x32x16_bf16 v[16:31], v[90:93], v[98:101], v[16:31]
	v_mfma_f32_32x32x16_bf16 v[0:15], v[102:105], v[106:109], v[0:15]
	v_mfma_f32_32x32x16_bf16 v[16:31], v[102:105], v[110:113], v[16:31]
	s_setprio 0
	s_mov_b32 m0, s70
	v_lshl_add_u64 v[66:67], v[36:37], 0, s[14:15]
	s_waitcnt vmcnt(0)
	s_waitcnt vmcnt(0)
	s_barrier
	global_load_lds_dwordx4 v[66:67], off
	v_lshl_add_u64 v[66:67], v[34:35], 0, s[14:15]
	s_mov_b32 m0, s61
	s_mov_b64 s[72:73], 0x20300
	global_load_lds_dwordx4 v[66:67], off
	v_lshl_add_u64 v[66:67], v[38:39], 0, s[14:15]
	s_mov_b32 m0, s62
	s_nop 0
	global_load_lds_dwordx4 v[66:67], off
	v_lshl_add_u64 v[66:67], v[40:41], 0, s[14:15]
	s_mov_b32 m0, s69
	s_nop 0
	global_load_lds_dwordx4 v[66:67], off
	v_lshl_add_u64 v[66:67], v[34:35], 0, s[72:73]
	s_mov_b32 m0, s68
	s_mov_b64 s[72:73], 0x30300
	global_load_lds_dwordx4 v[66:67], off
	v_lshl_add_u64 v[66:67], v[34:35], 0, s[72:73]
	s_mov_b32 m0, s63
	s_nop 0
	global_load_lds_dwordx4 v[66:67], off
	ds_read_b128 v[66:69], v45 offset:32768
	ds_read_b128 v[70:73], v46 offset:49152
	ds_read_b128 v[74:77], v46 offset:53248
	ds_read_b128 v[78:81], v47 offset:32768
	ds_read_b128 v[82:85], v48 offset:49152
	ds_read_b128 v[86:89], v48 offset:53248
	ds_read_b128 v[90:93], v49 offset:32768
	ds_read_b128 v[94:97], v50 offset:49152
	ds_read_b128 v[98:101], v50 offset:53248
	ds_read_b128 v[102:105], v51 offset:32768
	ds_read_b128 v[106:109], v52 offset:49152
	ds_read_b128 v[110:113], v52 offset:53248
	s_setprio 1
	s_waitcnt lgkmcnt(0)
	v_mfma_f32_32x32x16_bf16 v[0:15], v[66:69], v[70:73], v[0:15]
	v_mfma_f32_32x32x16_bf16 v[16:31], v[66:69], v[74:77], v[16:31]
	v_mfma_f32_32x32x16_bf16 v[0:15], v[78:81], v[82:85], v[0:15]
	v_mfma_f32_32x32x16_bf16 v[16:31], v[78:81], v[86:89], v[16:31]
	v_mfma_f32_32x32x16_bf16 v[0:15], v[90:93], v[94:97], v[0:15]
	v_mfma_f32_32x32x16_bf16 v[16:31], v[90:93], v[98:101], v[16:31]
	v_mfma_f32_32x32x16_bf16 v[0:15], v[102:105], v[106:109], v[0:15]
	v_mfma_f32_32x32x16_bf16 v[16:31], v[102:105], v[110:113], v[16:31]
	s_setprio 0
	s_mov_b32 m0, s58
	v_lshl_add_u64 v[66:67], v[36:37], 0, s[16:17]
	s_waitcnt vmcnt(0)
	s_waitcnt vmcnt(0)
	s_barrier
	global_load_lds_dwordx4 v[66:67], off
	v_lshl_add_u64 v[66:67], v[34:35], 0, s[16:17]
	s_mov_b32 m0, s41
	s_mov_b64 s[72:73], 0x20380
	global_load_lds_dwordx4 v[66:67], off
	v_lshl_add_u64 v[66:67], v[38:39], 0, s[16:17]
	s_mov_b32 m0, s56
	s_nop 0
	global_load_lds_dwordx4 v[66:67], off
	v_lshl_add_u64 v[66:67], v[40:41], 0, s[16:17]
	s_mov_b32 m0, s57
	s_nop 0
	global_load_lds_dwordx4 v[66:67], off
	v_lshl_add_u64 v[66:67], v[34:35], 0, s[72:73]
	s_mov_b32 m0, s59
	s_mov_b64 s[72:73], 0x30380
	global_load_lds_dwordx4 v[66:67], off
	v_lshl_add_u64 v[66:67], v[34:35], 0, s[72:73]
	s_mov_b32 m0, s60
	s_nop 0
	global_load_lds_dwordx4 v[66:67], off
	ds_read_b128 v[66:69], v45
	ds_read_b128 v[70:73], v46 offset:16384
	ds_read_b128 v[74:77], v46 offset:20480
	ds_read_b128 v[78:81], v47
	ds_read_b128 v[82:85], v48 offset:16384
	ds_read_b128 v[86:89], v48 offset:20480
	ds_read_b128 v[90:93], v49
	ds_read_b128 v[94:97], v50 offset:16384
	ds_read_b128 v[98:101], v50 offset:20480
	ds_read_b128 v[102:105], v51
	ds_read_b128 v[106:109], v52 offset:16384
	ds_read_b128 v[110:113], v52 offset:20480
	s_setprio 1
	s_waitcnt lgkmcnt(0)
	v_mfma_f32_32x32x16_bf16 v[0:15], v[66:69], v[70:73], v[0:15]
	v_mfma_f32_32x32x16_bf16 v[16:31], v[66:69], v[74:77], v[16:31]
	v_mfma_f32_32x32x16_bf16 v[0:15], v[78:81], v[82:85], v[0:15]
	v_mfma_f32_32x32x16_bf16 v[16:31], v[78:81], v[86:89], v[16:31]
	v_mfma_f32_32x32x16_bf16 v[0:15], v[90:93], v[94:97], v[0:15]
	v_mfma_f32_32x32x16_bf16 v[16:31], v[90:93], v[98:101], v[16:31]
	v_mfma_f32_32x32x16_bf16 v[0:15], v[102:105], v[106:109], v[0:15]
	v_mfma_f32_32x32x16_bf16 v[16:31], v[102:105], v[110:113], v[16:31]
	s_setprio 0
	s_mov_b32 m0, s70
	v_lshl_add_u64 v[66:67], v[36:37], 0, s[18:19]
	s_waitcnt vmcnt(0)
	s_waitcnt vmcnt(0)
	s_barrier
; #define MFMA(a, b, c) __builtin_amdgcn_mfma_f32_32x32x16_bf16((a), (b), (c), 0, 0, 0)
;     ...
;   for (int kt = 0; kt < NK; ++kt) {
;     asm volatile("s_waitcnt vmcnt(0)" ::: "memory");
;     __syncthreads();
;     const int cur = (kt & 1) * BUFB, nxt = BUFB - cur;
;     if (kt + 1 < NK) {
; #pragma unroll
;       for (int i = 0; i < 4; ++i) {
;         if (i < NA) __builtin_amdgcn_global_load_lds((const unsigned*)(ap[i] + (kt + 1) * 64), (unsigned*)(ldst + nxt + i * 4096), 16, 0, 0);
;         __builtin_amdgcn_global_load_lds((const unsigned*)(bp[i] + (kt + 1) * 64), (unsigned*)(ldst + nxt + OPB + i * 4096), 16, 0, 0);
;       }
;     }
;     const char* As = smem + cur; const char* Bs = smem + cur + OPB;
;     bf16x8 a[4][IM], b[4][2];
; #pragma unroll
;     for (int kk = 0; kk < 4; ++kk)
; #pragma unroll
;       for (int i = 0; i < 2; ++i) {
;         if (i < IM) a[kk][i] = *(const bf16x8*)(As + aoff[i] + (((2 * kk + h) ^ aswz[i]) << 4));
;         b[kk][i] = *(const bf16x8*)(Bs + boff[i] + (((2 * kk + h) ^ bswz[i]) << 4));
;       }
;     __builtin_amdgcn_sched_barrier(0);
;     __builtin_amdgcn_s_setprio(1);
; #pragma unroll
;     for (int kk = 0; kk < 4; ++kk)
; #pragma unroll
;       for (int i = 0; i < IM; ++i)
; #pragma unroll
;         for (int j = 0; j < 2; ++j) acc[i][j] = MFMA(a[kk][i], b[kk][j], acc[i][j]);
;     __builtin_amdgcn_s_setprio(0);
;   }
	global_load_lds_dwordx4 v[66:67], off
	v_lshl_add_u64 v[66:67], v[34:35], 0, s[18:19]
	s_mov_b32 m0, s61
	s_mov_b64 s[72:73], 0x20400
	global_load_lds_dwordx4 v[66:67], off
	v_lshl_add_u64 v[66:67], v[38:39], 0, s[18:19]
	s_mov_b32 m0, s62
	s_nop 0
	global_load_lds_dwordx4 v[66:67], off
	v_lshl_add_u64 v[66:67], v[40:41], 0, s[18:19]
	s_mov_b32 m0, s69
	s_nop 0
	global_load_lds_dwordx4 v[66:67], off
	v_lshl_add_u64 v[66:67], v[34:35], 0, s[72:73]
	s_mov_b32 m0, s68
	s_mov_b64 s[72:73], 0x30400
	global_load_lds_dwordx4 v[66:67], off
	v_lshl_add_u64 v[66:67], v[34:35], 0, s[72:73]
	s_mov_b32 m0, s63
	s_nop 0
	global_load_lds_dwordx4 v[66:67], off
	ds_read_b128 v[66:69], v45 offset:32768
	ds_read_b128 v[70:73], v46 offset:49152
	ds_read_b128 v[74:77], v46 offset:53248
	ds_read_b128 v[78:81], v47 offset:32768
	ds_read_b128 v[82:85], v48 offset:49152
	ds_read_b128 v[86:89], v48 offset:53248
	ds_read_b128 v[90:93], v49 offset:32768
	ds_read_b128 v[94:97], v50 offset:49152
	ds_read_b128 v[98:101], v50 offset:53248
	ds_read_b128 v[102:105], v51 offset:32768
	ds_read_b128 v[106:109], v52 offset:49152
	ds_read_b128 v[110:113], v52 offset:53248
	s_setprio 1
	s_waitcnt lgkmcnt(0)
	v_mfma_f32_32x32x16_bf16 v[0:15], v[66:69], v[70:73], v[0:15]
	v_mfma_f32_32x32x16_bf16 v[16:31], v[66:69], v[74:77], v[16:31]
	v_mfma_f32_32x32x16_bf16 v[0:15], v[78:81], v[82:85], v[0:15]
	v_mfma_f32_32x32x16_bf16 v[16:31], v[78:81], v[86:89], v[16:31]
	v_mfma_f32_32x32x16_bf16 v[0:15], v[90:93], v[94:97], v[0:15]
	v_mfma_f32_32x32x16_bf16 v[16:31], v[90:93], v[98:101], v[16:31]
	v_mfma_f32_32x32x16_bf16 v[0:15], v[102:105], v[106:109], v[0:15]
	v_mfma_f32_32x32x16_bf16 v[16:31], v[102:105], v[110:113], v[16:31]
	s_setprio 0
	s_mov_b32 m0, s58
	v_lshl_add_u64 v[66:67], v[36:37], 0, s[20:21]
	s_waitcnt vmcnt(0)
	s_waitcnt vmcnt(0)
	s_barrier
	global_load_lds_dwordx4 v[66:67], off
	v_lshl_add_u64 v[66:67], v[34:35], 0, s[20:21]
	s_mov_b32 m0, s41
	s_mov_b64 s[72:73], 0x20480
	global_load_lds_dwordx4 v[66:67], off
	v_lshl_add_u64 v[66:67], v[38:39], 0, s[20:21]
	s_mov_b32 m0, s56
	s_nop 0
	global_load_lds_dwordx4 v[66:67], off
	v_lshl_add_u64 v[66:67], v[40:41], 0, s[20:21]
	s_mov_b32 m0, s57
	s_nop 0
	global_load_lds_dwordx4 v[66:67], off
	v_lshl_add_u64 v[66:67], v[34:35], 0, s[72:73]
	s_mov_b32 m0, s59
	s_mov_b64 s[72:73], 0x30480
	global_load_lds_dwordx4 v[66:67], off
	v_lshl_add_u64 v[66:67], v[34:35], 0, s[72:73]
	s_mov_b32 m0, s60
	s_nop 0
	global_load_lds_dwordx4 v[66:67], off
	ds_read_b128 v[66:69], v45
	ds_read_b128 v[70:73], v46 offset:16384
	ds_read_b128 v[74:77], v46 offset:20480
	ds_read_b128 v[78:81], v47
	ds_read_b128 v[82:85], v48 offset:16384
	ds_read_b128 v[86:89], v48 offset:20480
	ds_read_b128 v[90:93], v49
	ds_read_b128 v[94:97], v50 offset:16384
	ds_read_b128 v[98:101], v50 offset:20480
	ds_read_b128 v[102:105], v51
	ds_read_b128 v[106:109], v52 offset:16384
	ds_read_b128 v[110:113], v52 offset:20480
	s_setprio 1
	s_waitcnt lgkmcnt(0)
	v_mfma_f32_32x32x16_bf16 v[0:15], v[66:69], v[70:73], v[0:15]
	v_mfma_f32_32x32x16_bf16 v[16:31], v[66:69], v[74:77], v[16:31]
	v_mfma_f32_32x32x16_bf16 v[0:15], v[78:81], v[82:85], v[0:15]
	v_mfma_f32_32x32x16_bf16 v[16:31], v[78:81], v[86:89], v[16:31]
	v_mfma_f32_32x32x16_bf16 v[0:15], v[90:93], v[94:97], v[0:15]
	v_mfma_f32_32x32x16_bf16 v[16:31], v[90:93], v[98:101], v[16:31]
	v_mfma_f32_32x32x16_bf16 v[0:15], v[102:105], v[106:109], v[0:15]
	v_mfma_f32_32x32x16_bf16 v[16:31], v[102:105], v[110:113], v[16:31]
	s_setprio 0
	s_mov_b32 m0, s70
	v_lshl_add_u64 v[66:67], v[36:37], 0, s[22:23]
	s_waitcnt vmcnt(0)
	s_waitcnt vmcnt(0)
	s_barrier
	global_load_lds_dwordx4 v[66:67], off
	v_lshl_add_u64 v[66:67], v[34:35], 0, s[22:23]
	s_mov_b32 m0, s61
	s_mov_b64 s[70:71], 0x20500
	global_load_lds_dwordx4 v[66:67], off
	v_lshl_add_u64 v[66:67], v[38:39], 0, s[22:23]
	s_mov_b32 m0, s62
	s_nop 0
	global_load_lds_dwordx4 v[66:67], off
	v_lshl_add_u64 v[66:67], v[40:41], 0, s[22:23]
	s_mov_b32 m0, s69
	s_nop 0
	global_load_lds_dwordx4 v[66:67], off
	v_lshl_add_u64 v[66:67], v[34:35], 0, s[70:71]
	s_mov_b32 m0, s68
	s_mov_b64 s[68:69], 0x30500
	global_load_lds_dwordx4 v[66:67], off
	v_lshl_add_u64 v[66:67], v[34:35], 0, s[68:69]
	s_mov_b32 m0, s63
	s_nop 0
	global_load_lds_dwordx4 v[66:67], off
	ds_read_b128 v[66:69], v45 offset:32768
	ds_read_b128 v[70:73], v46 offset:49152
	ds_read_b128 v[74:77], v46 offset:53248
	ds_read_b128 v[78:81], v47 offset:32768
	ds_read_b128 v[82:85], v48 offset:49152
	ds_read_b128 v[86:89], v48 offset:53248
	ds_read_b128 v[90:93], v49 offset:32768
	ds_read_b128 v[94:97], v50 offset:49152
	ds_read_b128 v[98:101], v50 offset:53248
	ds_read_b128 v[102:105], v51 offset:32768
	ds_read_b128 v[106:109], v52 offset:49152
	ds_read_b128 v[110:113], v52 offset:53248
	s_setprio 1
	s_waitcnt lgkmcnt(0)
	v_mfma_f32_32x32x16_bf16 v[0:15], v[66:69], v[70:73], v[0:15]
	v_mfma_f32_32x32x16_bf16 v[16:31], v[66:69], v[74:77], v[16:31]
	v_mfma_f32_32x32x16_bf16 v[0:15], v[78:81], v[82:85], v[0:15]
	v_mfma_f32_32x32x16_bf16 v[16:31], v[78:81], v[86:89], v[16:31]
	v_mfma_f32_32x32x16_bf16 v[0:15], v[90:93], v[94:97], v[0:15]
	v_mfma_f32_32x32x16_bf16 v[16:31], v[90:93], v[98:101], v[16:31]
	v_mfma_f32_32x32x16_bf16 v[0:15], v[102:105], v[106:109], v[0:15]
	v_mfma_f32_32x32x16_bf16 v[16:31], v[102:105], v[110:113], v[16:31]
	s_setprio 0
	s_mov_b32 m0, s58
	v_lshl_add_u64 v[66:67], v[36:37], 0, s[24:25]
	s_waitcnt vmcnt(0)
	s_waitcnt vmcnt(0)
	s_barrier
; #define MFMA(a, b, c) __builtin_amdgcn_mfma_f32_32x32x16_bf16((a), (b), (c), 0, 0, 0)
;     ...
;   for (int kt = 0; kt < NK; ++kt) {
;     asm volatile("s_waitcnt vmcnt(0)" ::: "memory");
;     __syncthreads();
;     const int cur = (kt & 1) * BUFB, nxt = BUFB - cur;
;     if (kt + 1 < NK) {
; #pragma unroll
;       for (int i = 0; i < 4; ++i) {
;         if (i < NA) __builtin_amdgcn_global_load_lds((const unsigned*)(ap[i] + (kt + 1) * 64), (unsigned*)(ldst + nxt + i * 4096), 16, 0, 0);
;         __builtin_amdgcn_global_load_lds((const unsigned*)(bp[i] + (kt + 1) * 64), (unsigned*)(ldst + nxt + OPB + i * 4096), 16, 0, 0);
;       }
;     }
;     const char* As = smem + cur; const char* Bs = smem + cur + OPB;
;     bf16x8 a[4][IM], b[4][2];
; #pragma unroll
;     for (int kk = 0; kk < 4; ++kk)
; #pragma unroll
;       for (int i = 0; i < 2; ++i) {
;         if (i < IM) a[kk][i] = *(const bf16x8*)(As + aoff[i] + (((2 * kk + h) ^ aswz[i]) << 4));
;         b[kk][i] = *(const bf16x8*)(Bs + boff[i] + (((2 * kk + h) ^ bswz[i]) << 4));
;       }
;     __builtin_amdgcn_sched_barrier(0);
;     __builtin_amdgcn_s_setprio(1);
; #pragma unroll
;     for (int kk = 0; kk < 4; ++kk)
; #pragma unroll
;       for (int i = 0; i < IM; ++i)
; #pragma unroll
;         for (int j = 0; j < 2; ++j) acc[i][j] = MFMA(a[kk][i], b[kk][j], acc[i][j]);
;     __builtin_amdgcn_s_setprio(0);
;   }
	global_load_lds_dwordx4 v[66:67], off
	v_lshl_add_u64 v[66:67], v[34:35], 0, s[24:25]
	s_mov_b32 m0, s41
	s_nop 0
	global_load_lds_dwordx4 v[66:67], off
	v_lshl_add_u64 v[66:67], v[38:39], 0, s[24:25]
	s_mov_b32 m0, s56
	s_nop 0
	global_load_lds_dwordx4 v[66:67], off
	v_lshl_add_u64 v[66:67], v[40:41], 0, s[24:25]
	s_mov_b32 m0, s57
	s_mov_b64 s[56:57], 0x20580
	global_load_lds_dwordx4 v[66:67], off
	v_lshl_add_u64 v[66:67], v[34:35], 0, s[56:57]
	s_mov_b32 m0, s59
	s_mov_b64 s[56:57], 0x30580
	global_load_lds_dwordx4 v[66:67], off
	v_lshl_add_u64 v[66:67], v[34:35], 0, s[56:57]
	s_mov_b32 m0, s60
	s_nop 0
	global_load_lds_dwordx4 v[66:67], off
	ds_read_b128 v[66:69], v45
	ds_read_b128 v[70:73], v46 offset:16384
	ds_read_b128 v[74:77], v46 offset:20480
	ds_read_b128 v[78:81], v47
	ds_read_b128 v[82:85], v48 offset:16384
	ds_read_b128 v[86:89], v48 offset:20480
	ds_read_b128 v[90:93], v49
	ds_read_b128 v[94:97], v50 offset:16384
	ds_read_b128 v[98:101], v50 offset:20480
	ds_read_b128 v[102:105], v51
	ds_read_b128 v[106:109], v52 offset:16384
	ds_read_b128 v[110:113], v52 offset:20480
	s_setprio 1
	s_waitcnt lgkmcnt(0)
	v_mfma_f32_32x32x16_bf16 v[0:15], v[66:69], v[70:73], v[0:15]
	v_mfma_f32_32x32x16_bf16 v[16:31], v[66:69], v[74:77], v[16:31]
	v_mfma_f32_32x32x16_bf16 v[0:15], v[78:81], v[82:85], v[0:15]
	v_mfma_f32_32x32x16_bf16 v[16:31], v[78:81], v[86:89], v[16:31]
	v_mfma_f32_32x32x16_bf16 v[0:15], v[90:93], v[94:97], v[0:15]
	v_mfma_f32_32x32x16_bf16 v[16:31], v[90:93], v[98:101], v[16:31]
	v_mfma_f32_32x32x16_bf16 v[0:15], v[102:105], v[106:109], v[0:15]
	v_mfma_f32_32x32x16_bf16 v[16:31], v[102:105], v[110:113], v[16:31]
	s_setprio 0
	v_readfirstlane_b32 s41, v59
	v_lshl_add_u64 v[66:67], v[36:37], 0, s[26:27]
	s_mov_b32 m0, s41
	v_readfirstlane_b32 s58, v60
	s_waitcnt vmcnt(0)
	s_waitcnt vmcnt(0)
	s_barrier
	global_load_lds_dwordx4 v[66:67], off
	v_lshl_add_u64 v[66:67], v[34:35], 0, s[26:27]
	s_mov_b32 m0, s58
	v_readfirstlane_b32 s59, v63
	global_load_lds_dwordx4 v[66:67], off
	v_lshl_add_u64 v[66:67], v[38:39], 0, s[26:27]
	s_mov_b32 m0, s59
	v_readfirstlane_b32 s60, v64
	global_load_lds_dwordx4 v[66:67], off
	v_lshl_add_u64 v[66:67], v[40:41], 0, s[26:27]
	s_mov_b32 m0, s60
	s_mov_b64 s[56:57], 0x20600
	v_readfirstlane_b32 s61, v62
	global_load_lds_dwordx4 v[66:67], off
	v_lshl_add_u64 v[64:65], v[34:35], 0, s[56:57]
	s_mov_b32 m0, s61
	s_mov_b64 s[56:57], 0x30600
	v_readfirstlane_b32 s62, v61
	global_load_lds_dwordx4 v[64:65], off
	v_lshl_add_u64 v[62:63], v[34:35], 0, s[56:57]
	s_mov_b32 m0, s62
	s_nop 0
	global_load_lds_dwordx4 v[62:63], off
	ds_read_b128 v[60:63], v45 offset:32768
	ds_read_b128 v[64:67], v46 offset:49152
	ds_read_b128 v[68:71], v46 offset:53248
	ds_read_b128 v[72:75], v47 offset:32768
	ds_read_b128 v[76:79], v48 offset:49152
	ds_read_b128 v[80:83], v48 offset:53248
	ds_read_b128 v[84:87], v49 offset:32768
	ds_read_b128 v[88:91], v50 offset:49152
	ds_read_b128 v[92:95], v50 offset:53248
	ds_read_b128 v[96:99], v51 offset:32768
	ds_read_b128 v[100:103], v52 offset:49152
	ds_read_b128 v[104:107], v52 offset:53248
	s_setprio 1
	s_waitcnt lgkmcnt(0)
	v_mfma_f32_32x32x16_bf16 v[0:15], v[60:63], v[64:67], v[0:15]
	v_mfma_f32_32x32x16_bf16 v[16:31], v[60:63], v[68:71], v[16:31]
	v_mfma_f32_32x32x16_bf16 v[0:15], v[72:75], v[76:79], v[0:15]
	v_mfma_f32_32x32x16_bf16 v[16:31], v[72:75], v[80:83], v[16:31]
	v_mfma_f32_32x32x16_bf16 v[0:15], v[84:87], v[88:91], v[0:15]
	v_mfma_f32_32x32x16_bf16 v[16:31], v[84:87], v[92:95], v[16:31]
	v_mfma_f32_32x32x16_bf16 v[0:15], v[96:99], v[100:103], v[0:15]
	v_mfma_f32_32x32x16_bf16 v[16:31], v[96:99], v[104:107], v[16:31]
	s_setprio 0
	v_readfirstlane_b32 s63, v54
	v_lshl_add_u64 v[60:61], v[36:37], 0, s[28:29]
	s_mov_b32 m0, s63
	v_readfirstlane_b32 s68, v53
	s_waitcnt vmcnt(0)
	s_waitcnt vmcnt(0)
	s_barrier
	global_load_lds_dwordx4 v[60:61], off
	v_lshl_add_u64 v[60:61], v[34:35], 0, s[28:29]
	s_mov_b32 m0, s68
	v_readfirstlane_b32 s69, v55
	global_load_lds_dwordx4 v[60:61], off
	v_lshl_add_u64 v[60:61], v[38:39], 0, s[28:29]
	s_mov_b32 m0, s69
	v_readfirstlane_b32 s70, v56
	global_load_lds_dwordx4 v[60:61], off
	v_lshl_add_u64 v[54:55], v[40:41], 0, s[28:29]
	s_mov_b32 m0, s70
	s_mov_b64 s[56:57], 0x20680
	v_readfirstlane_b32 s71, v57
	global_load_lds_dwordx4 v[54:55], off
	v_lshl_add_u64 v[54:55], v[34:35], 0, s[56:57]
	s_mov_b32 m0, s71
	s_mov_b64 s[56:57], 0x30680
	v_readfirstlane_b32 s72, v58
	global_load_lds_dwordx4 v[54:55], off
	v_lshl_add_u64 v[54:55], v[34:35], 0, s[56:57]
	s_mov_b32 m0, s72
	s_nop 0
	global_load_lds_dwordx4 v[54:55], off
	ds_read_b128 v[54:57], v45
	ds_read_b128 v[58:61], v46 offset:16384
	ds_read_b128 v[62:65], v46 offset:20480
	ds_read_b128 v[66:69], v47
	ds_read_b128 v[70:73], v48 offset:16384
	ds_read_b128 v[74:77], v48 offset:20480
	ds_read_b128 v[78:81], v49
	ds_read_b128 v[82:85], v50 offset:16384
	ds_read_b128 v[86:89], v50 offset:20480
	ds_read_b128 v[90:93], v51
	ds_read_b128 v[94:97], v52 offset:16384
	ds_read_b128 v[98:101], v52 offset:20480
	s_setprio 1
	s_waitcnt lgkmcnt(0)
	v_mfma_f32_32x32x16_bf16 v[0:15], v[54:57], v[58:61], v[0:15]
	v_mfma_f32_32x32x16_bf16 v[16:31], v[54:57], v[62:65], v[16:31]
	v_mfma_f32_32x32x16_bf16 v[0:15], v[66:69], v[70:73], v[0:15]
	v_mfma_f32_32x32x16_bf16 v[16:31], v[66:69], v[74:77], v[16:31]
	v_mfma_f32_32x32x16_bf16 v[0:15], v[78:81], v[82:85], v[0:15]
	v_mfma_f32_32x32x16_bf16 v[16:31], v[78:81], v[86:89], v[16:31]
	v_mfma_f32_32x32x16_bf16 v[0:15], v[90:93], v[94:97], v[0:15]
	v_mfma_f32_32x32x16_bf16 v[16:31], v[90:93], v[98:101], v[16:31]
	s_setprio 0
	s_mov_b32 m0, s41
	v_lshl_add_u64 v[54:55], v[36:37], 0, s[30:31]
	s_waitcnt vmcnt(0)
	s_waitcnt vmcnt(0)
	s_barrier
; #define MFMA(a, b, c) __builtin_amdgcn_mfma_f32_32x32x16_bf16((a), (b), (c), 0, 0, 0)
; DI int crow(int reg, int h) { return (reg & 3) + 8 * (reg >> 2) + 4 * h; }
;     ...
;   for (int kt = 0; kt < NK; ++kt) {
;     asm volatile("s_waitcnt vmcnt(0)" ::: "memory");
;     __syncthreads();
;     const int cur = (kt & 1) * BUFB, nxt = BUFB - cur;
;     if (kt + 1 < NK) {
; #pragma unroll
;       for (int i = 0; i < 4; ++i) {
;         if (i < NA) __builtin_amdgcn_global_load_lds((const unsigned*)(ap[i] + (kt + 1) * 64), (unsigned*)(ldst + nxt + i * 4096), 16, 0, 0);
;         __builtin_amdgcn_global_load_lds((const unsigned*)(bp[i] + (kt + 1) * 64), (unsigned*)(ldst + nxt + OPB + i * 4096), 16, 0, 0);
;       }
;     }
;     const char* As = smem + cur; const char* Bs = smem + cur + OPB;
;     bf16x8 a[4][IM], b[4][2];
; #pragma unroll
;     for (int kk = 0; kk < 4; ++kk)
; #pragma unroll
;       for (int i = 0; i < 2; ++i) {
;         if (i < IM) a[kk][i] = *(const bf16x8*)(As + aoff[i] + (((2 * kk + h) ^ aswz[i]) << 4));
;         b[kk][i] = *(const bf16x8*)(Bs + boff[i] + (((2 * kk + h) ^ bswz[i]) << 4));
;       }
;     __builtin_amdgcn_sched_barrier(0);
;     __builtin_amdgcn_s_setprio(1);
; #pragma unroll
;     for (int kk = 0; kk < 4; ++kk)
; #pragma unroll
;       for (int i = 0; i < IM; ++i)
; #pragma unroll
;         for (int j = 0; j < 2; ++j) acc[i][j] = MFMA(a[kk][i], b[kk][j], acc[i][j]);
;     __builtin_amdgcn_s_setprio(0);
;   }
;   __syncthreads();
;   float* Cs = (float*)smem;
; #pragma unroll
;   for (int i = 0; i < IM; ++i)
; #pragma unroll
;     for (int j = 0; j < 2; ++j)
; #pragma unroll
;       for (int e = 0; e < 16; ++e) Cs[(wm * (BM / 2) + i * 32 + crow(e, h)) * CS_LD + wn * 64 + j * 32 + r] = acc[i][j][e];
	global_load_lds_dwordx4 v[54:55], off
	v_lshl_add_u64 v[54:55], v[34:35], 0, s[30:31]
	s_mov_b32 m0, s58
	s_mov_b64 s[56:57], 0x20700
	global_load_lds_dwordx4 v[54:55], off
	v_lshl_add_u64 v[54:55], v[38:39], 0, s[30:31]
	s_mov_b32 m0, s59
	s_nop 0
	global_load_lds_dwordx4 v[54:55], off
	v_lshl_add_u64 v[54:55], v[40:41], 0, s[30:31]
	s_mov_b32 m0, s60
	s_nop 0
	global_load_lds_dwordx4 v[54:55], off
	v_lshl_add_u64 v[54:55], v[34:35], 0, s[56:57]
	s_mov_b32 m0, s61
	s_mov_b64 s[56:57], 0x30700
	global_load_lds_dwordx4 v[54:55], off
	v_lshl_add_u64 v[54:55], v[34:35], 0, s[56:57]
	s_mov_b32 m0, s62
	s_nop 0
	global_load_lds_dwordx4 v[54:55], off
	ds_read_b128 v[54:57], v45 offset:32768
	ds_read_b128 v[58:61], v46 offset:49152
	ds_read_b128 v[62:65], v46 offset:53248
	ds_read_b128 v[66:69], v47 offset:32768
	ds_read_b128 v[70:73], v48 offset:49152
	ds_read_b128 v[74:77], v48 offset:53248
	ds_read_b128 v[78:81], v49 offset:32768
	ds_read_b128 v[82:85], v50 offset:49152
	ds_read_b128 v[86:89], v50 offset:53248
	ds_read_b128 v[90:93], v51 offset:32768
	ds_read_b128 v[94:97], v52 offset:49152
	ds_read_b128 v[98:101], v52 offset:53248
	s_setprio 1
	s_waitcnt lgkmcnt(0)
	v_mfma_f32_32x32x16_bf16 v[0:15], v[54:57], v[58:61], v[0:15]
	v_mfma_f32_32x32x16_bf16 v[16:31], v[54:57], v[62:65], v[16:31]
	v_mfma_f32_32x32x16_bf16 v[0:15], v[66:69], v[70:73], v[0:15]
	v_mfma_f32_32x32x16_bf16 v[16:31], v[66:69], v[74:77], v[16:31]
	v_mfma_f32_32x32x16_bf16 v[0:15], v[78:81], v[82:85], v[0:15]
	v_mfma_f32_32x32x16_bf16 v[16:31], v[78:81], v[86:89], v[16:31]
	v_mfma_f32_32x32x16_bf16 v[0:15], v[90:93], v[94:97], v[0:15]
	v_mfma_f32_32x32x16_bf16 v[16:31], v[90:93], v[98:101], v[16:31]
	s_setprio 0
	s_mov_b32 m0, s63
	v_lshl_add_u64 v[36:37], v[36:37], 0, s[34:35]
	s_waitcnt vmcnt(0)
	s_waitcnt vmcnt(0)
	s_barrier
	global_load_lds_dwordx4 v[36:37], off
	v_lshl_add_u64 v[36:37], v[34:35], 0, s[34:35]
	s_mov_b32 m0, s68
	s_mov_b64 s[56:57], 0x20780
	global_load_lds_dwordx4 v[36:37], off
	v_lshl_add_u64 v[36:37], v[38:39], 0, s[34:35]
	s_mov_b32 m0, s69
	s_nop 0
	global_load_lds_dwordx4 v[36:37], off
	v_lshl_add_u64 v[36:37], v[40:41], 0, s[34:35]
	s_mov_b32 m0, s70
	s_nop 0
	global_load_lds_dwordx4 v[36:37], off
	v_lshl_add_u64 v[36:37], v[34:35], 0, s[56:57]
	s_mov_b32 m0, s71
	s_mov_b64 s[56:57], 0x30780
	global_load_lds_dwordx4 v[36:37], off
	v_lshl_add_u64 v[34:35], v[34:35], 0, s[56:57]
	s_mov_b32 m0, s72
	s_nop 0
	global_load_lds_dwordx4 v[34:35], off
	ds_read_b128 v[34:37], v45
	ds_read_b128 v[38:41], v46 offset:16384
	ds_read_b128 v[54:57], v46 offset:20480
	ds_read_b128 v[58:61], v47
	ds_read_b128 v[62:65], v48 offset:16384
	ds_read_b128 v[66:69], v48 offset:20480
	ds_read_b128 v[70:73], v49
	ds_read_b128 v[74:77], v50 offset:16384
	ds_read_b128 v[78:81], v50 offset:20480
	ds_read_b128 v[82:85], v51
	ds_read_b128 v[86:89], v52 offset:16384
	ds_read_b128 v[90:93], v52 offset:20480
	s_setprio 1
	s_waitcnt lgkmcnt(0)
	v_mfma_f32_32x32x16_bf16 v[0:15], v[34:37], v[38:41], v[0:15]
	v_mfma_f32_32x32x16_bf16 v[16:31], v[34:37], v[54:57], v[16:31]
	v_mfma_f32_32x32x16_bf16 v[0:15], v[58:61], v[62:65], v[0:15]
	v_mfma_f32_32x32x16_bf16 v[16:31], v[58:61], v[66:69], v[16:31]
	v_mfma_f32_32x32x16_bf16 v[0:15], v[70:73], v[74:77], v[0:15]
	v_mfma_f32_32x32x16_bf16 v[16:31], v[70:73], v[78:81], v[16:31]
	v_mfma_f32_32x32x16_bf16 v[0:15], v[82:85], v[86:89], v[0:15]
	v_mfma_f32_32x32x16_bf16 v[16:31], v[82:85], v[90:93], v[16:31]
	s_setprio 0
	s_waitcnt vmcnt(0)
	s_waitcnt vmcnt(0)
	s_barrier
	ds_read_b128 v[34:37], v45 offset:32768
	ds_read_b128 v[38:41], v46 offset:49152
	ds_read_b128 v[54:57], v46 offset:53248
	ds_read_b128 v[58:61], v47 offset:32768
	ds_read_b128 v[62:65], v48 offset:49152
	ds_read_b128 v[66:69], v48 offset:53248
	ds_read_b128 v[46:49], v49 offset:32768
	ds_read_b128 v[70:73], v50 offset:49152
	ds_read_b128 v[74:77], v50 offset:53248
	ds_read_b128 v[78:81], v51 offset:32768
	ds_read_b128 v[82:85], v52 offset:49152
	ds_read_b128 v[50:53], v52 offset:53248
	s_setprio 1
	s_waitcnt lgkmcnt(10)
	v_mfma_f32_32x32x16_bf16 v[0:15], v[34:37], v[38:41], v[0:15]
	s_waitcnt lgkmcnt(9)
	v_mfma_f32_32x32x16_bf16 v[16:31], v[34:37], v[54:57], v[16:31]
	s_waitcnt lgkmcnt(7)
	v_mfma_f32_32x32x16_bf16 v[0:15], v[58:61], v[62:65], v[0:15]
	s_waitcnt lgkmcnt(6)
	v_mfma_f32_32x32x16_bf16 v[16:31], v[58:61], v[66:69], v[16:31]
	s_waitcnt lgkmcnt(4)
	v_mfma_f32_32x32x16_bf16 v[0:15], v[46:49], v[70:73], v[0:15]
	s_waitcnt lgkmcnt(3)
	v_mfma_f32_32x32x16_bf16 v[16:31], v[46:49], v[74:77], v[16:31]
	s_waitcnt lgkmcnt(1)
	v_mfma_f32_32x32x16_bf16 v[0:15], v[78:81], v[82:85], v[0:15]
	s_waitcnt lgkmcnt(0)
	v_mfma_f32_32x32x16_bf16 v[16:31], v[78:81], v[50:53], v[16:31]
	s_setprio 0
	v_lshlrev_b32_e32 v34, 5, v42
	v_lshlrev_b32_e32 v35, 8, v44
	v_lshl_or_b32 v34, v43, 2, v34
	v_lshl_or_b32 v32, v32, 2, v35
	v_mad_u64_u32 v[34:35], s[56:57], v34, s47, v[32:33]
	s_barrier
;   DI u16* y0b() const { return (u16*)(ws + WS_y0b); }
;   DI float* pre() const { return (float*)(ws + WS_pre); }
; DI float bflo(unsigned v) { return __uint_as_float(v << 16); }
; DI float bfhi(unsigned v) { return __uint_as_float(v & 0xffff0000u); }
; DI int otid() { int t = threadIdx.x; asm volatile("" : "+v"(t)); return t; }
; DI int crow(int reg, int h) { return (reg & 3) + 8 * (reg >> 2) + 4 * h; }
; DI void st_bf4(u16* d, float a, float b, float c, float e) { *(uint2*)d = pack4(a, b, c, e); }
;     ...
;   __syncthreads();
;   float* Cs = (float*)smem;
; #pragma unroll
;   for (int i = 0; i < IM; ++i)
; #pragma unroll
;     for (int j = 0; j < 2; ++j)
; #pragma unroll
;       for (int e = 0; e < 16; ++e) Cs[(wm * (BM / 2) + i * 32 + crow(e, h)) * CS_LD + wn * 64 + j * 32 + r] = acc[i][j][e];
;   __syncthreads();
;   const int tid = otid(), c4 = (tid & 31) * 4;
;   for (int pp = 0; pp < npass; ++pp) {
;     const int row = pp * 8 + (tid >> 5);
;     const int tok = mt * 128 + row0 + row;
;     const int col = nt * 128 + c4;
;     float4 v = *(const float4*)(Cs + row * CS_LD + c4);
;     float4 x;
;     if (layer == 0) { const f32x4 t = __builtin_nontemporal_load((const f32x4*)(tok < TP ? p.x_prompt + (size_t)tok * 1024 + col : p.x_sample + (size_t)(tok - TP) * 1024 + col)); x = make_float4(t[0], t[1], t[2], t[3]); }
;     else { const uint2 yb = *(const uint2*)(p.y0b() + (size_t)tok * 1024 + col); x = make_float4(bflo(yb.x), bfhi(yb.x), bflo(yb.y), bfhi(yb.y)); }
;     st_bf4((u16*)p.pre() + (size_t)tok * 1024 + col, ALPHA * x.x + v.x, ALPHA * x.y + v.y, ALPHA * x.z + v.z, ALPHA * x.w + v.w);
;   }
	s_nop 4
	ds_write2_b32 v34, v0, v16 offset1:32
	ds_write2_b32 v34, v1, v17 offset0:132 offset1:164
	v_add_u32_e32 v0, 0x400, v34
	ds_write2_b32 v0, v2, v18 offset0:8 offset1:40
	ds_write2_b32 v0, v3, v19 offset0:140 offset1:172
	v_add_u32_e32 v0, 0x1000, v34
	ds_write2_b32 v0, v4, v20 offset0:32 offset1:64
	ds_write2_b32 v0, v5, v21 offset0:164 offset1:196
	v_add_u32_e32 v0, 0x1400, v34
	ds_write2_b32 v0, v6, v22 offset0:40 offset1:72
	ds_write2_b32 v0, v7, v23 offset0:172 offset1:204
	v_add_u32_e32 v0, 0x2000, v34
	ds_write2_b32 v0, v8, v24 offset0:64 offset1:96
	ds_write2_b32 v0, v9, v25 offset0:196 offset1:228
	v_add_u32_e32 v0, 0x2400, v34
	ds_write2_b32 v0, v10, v26 offset0:72 offset1:104
	ds_write2_b32 v0, v11, v27 offset0:204 offset1:236
	v_add_u32_e32 v0, 0x3000, v34
	ds_write2_b32 v0, v12, v28 offset0:96 offset1:128
	v_add_u32_e32 v0, 0x3200, v34
	ds_write2_b32 v0, v13, v29 offset0:100 offset1:132
	v_add_u32_e32 v0, 0x3400, v34
	ds_write2_b32 v0, v14, v30 offset0:104 offset1:136
	v_add_u32_e32 v0, 0x3600, v34
	ds_write2_b32 v0, v15, v31 offset0:108 offset1:140
	v_mov_b32_e32 v0, v186
	s_waitcnt lgkmcnt(0)
	s_barrier
	s_mov_b32 s59, s40
	v_lshlrev_b32_e32 v220, 2, v186
	v_and_b32_e32 v220, 0x7c, v220
	v_ashrrev_i32_e32 v221, 5, v186
	v_mul_lo_u32 v222, v221, s47
	v_lshl_add_u32 v222, v220, 2, v222
	v_lshlrev_b32_e32 v223, 12, v221
	v_lshl_add_u32 v223, v220, 2, v223
	v_lshlrev_b32_e32 v224, 11, v221
	v_lshl_add_u32 v224, v220, 1, v224
	s_cmp_gt_i32 s59, s48
	s_cselect_b32 s40, s54, s52
	s_cselect_b32 s41, s55, s53
	s_cselect_b32 s58, 0x4000, 0
	s_sub_i32 s58, s59, s58
	s_lshl_b32 s58, s58, 12
	s_add_u32 s40, s40, s58
	s_addc_u32 s41, s41, 0
	s_lshl_b32 s58, s49, 2
	s_add_u32 s40, s40, s58
	s_addc_u32 s41, s41, 0
	s_lshl_b32 s58, s59, 11
	s_add_u32 s56, s2, s58
	s_addc_u32 s57, s3, 0
	s_lshl_b32 s58, s49, 1
	s_add_u32 s56, s56, s58
	s_addc_u32 s57, s57, 0
	ds_read_b128 v[228:231], v222
	ds_read_b128 v[232:235], v222 offset:4224
	ds_read_b128 v[236:239], v222 offset:8448
	ds_read_b128 v[240:243], v222 offset:12672
	global_load_dwordx4 v[154:157], v223, s[40:41] nt
	s_add_u32 s40, s40, 0x8000
	s_addc_u32 s41, s41, 0
	global_load_dwordx4 v[158:161], v223, s[40:41] nt
	s_add_u32 s40, s40, 0x8000
	s_addc_u32 s41, s41, 0
	global_load_dwordx4 v[162:165], v223, s[40:41] nt
	s_add_u32 s40, s40, 0x8000
	s_addc_u32 s41, s41, 0
	global_load_dwordx4 v[166:169], v223, s[40:41] nt
	s_add_u32 s40, s40, 0x8000
	s_addc_u32 s41, s41, 0
	global_load_dwordx4 v[170:173], v223, s[40:41] nt
	s_add_u32 s40, s40, 0x8000
	s_addc_u32 s41, s41, 0
	global_load_dwordx4 v[174:177], v223, s[40:41] nt
	s_add_u32 s40, s40, 0x8000
	s_addc_u32 s41, s41, 0
	global_load_dwordx4 v[178:181], v223, s[40:41] nt
	s_add_u32 s40, s40, 0x8000
	s_addc_u32 s41, s41, 0
	global_load_dwordx4 v[182:185], v223, s[40:41] nt
	s_waitcnt vmcnt(7) lgkmcnt(3)
	v_pk_fma_f32 v[228:229], v[154:155], s[36:37], v[228:229] op_sel_hi:[1,0,1]
	v_pk_fma_f32 v[230:231], v[156:157], s[36:37], v[230:231] op_sel_hi:[1,0,1]
	v_cvt_pk_bf16_f32 v244, v228, v229
	v_cvt_pk_bf16_f32 v245, v230, v231
	global_store_dwordx2 v224, v[244:245], s[56:57]
	s_add_u32 s56, s56, 0x4000
	s_addc_u32 s57, s57, 0
	ds_read_b128 v[228:231], v222 offset:16896
	s_waitcnt vmcnt(7) lgkmcnt(3)
	v_pk_fma_f32 v[232:233], v[158:159], s[36:37], v[232:233] op_sel_hi:[1,0,1]
	v_pk_fma_f32 v[234:235], v[160:161], s[36:37], v[234:235] op_sel_hi:[1,0,1]
	v_cvt_pk_bf16_f32 v226, v232, v233
	v_cvt_pk_bf16_f32 v227, v234, v235
	global_store_dwordx2 v224, v[226:227], s[56:57]
	s_add_u32 s56, s56, 0x4000
	s_addc_u32 s57, s57, 0
	ds_read_b128 v[232:235], v222 offset:21120
	s_waitcnt vmcnt(7) lgkmcnt(3)
	v_pk_fma_f32 v[236:237], v[162:163], s[36:37], v[236:237] op_sel_hi:[1,0,1]
	v_pk_fma_f32 v[238:239], v[164:165], s[36:37], v[238:239] op_sel_hi:[1,0,1]
	v_cvt_pk_bf16_f32 v244, v236, v237
	v_cvt_pk_bf16_f32 v245, v238, v239
	global_store_dwordx2 v224, v[244:245], s[56:57]
	s_add_u32 s56, s56, 0x4000
	s_addc_u32 s57, s57, 0
	ds_read_b128 v[236:239], v222 offset:25344
	s_waitcnt vmcnt(7) lgkmcnt(3)
	v_pk_fma_f32 v[240:241], v[166:167], s[36:37], v[240:241] op_sel_hi:[1,0,1]
	v_pk_fma_f32 v[242:243], v[168:169], s[36:37], v[242:243] op_sel_hi:[1,0,1]
	v_cvt_pk_bf16_f32 v226, v240, v241
	v_cvt_pk_bf16_f32 v227, v242, v243
	global_store_dwordx2 v224, v[226:227], s[56:57]
	s_add_u32 s56, s56, 0x4000
	s_addc_u32 s57, s57, 0
	ds_read_b128 v[240:243], v222 offset:29568
	s_waitcnt vmcnt(7) lgkmcnt(3)
	v_pk_fma_f32 v[228:229], v[170:171], s[36:37], v[228:229] op_sel_hi:[1,0,1]
	v_pk_fma_f32 v[230:231], v[172:173], s[36:37], v[230:231] op_sel_hi:[1,0,1]
	v_cvt_pk_bf16_f32 v244, v228, v229
	v_cvt_pk_bf16_f32 v245, v230, v231
	global_store_dwordx2 v224, v[244:245], s[56:57]
	s_add_u32 s56, s56, 0x4000
	s_addc_u32 s57, s57, 0
	s_waitcnt vmcnt(7) lgkmcnt(2)
	v_pk_fma_f32 v[232:233], v[174:175], s[36:37], v[232:233] op_sel_hi:[1,0,1]
	v_pk_fma_f32 v[234:235], v[176:177], s[36:37], v[234:235] op_sel_hi:[1,0,1]
	v_cvt_pk_bf16_f32 v226, v232, v233
	v_cvt_pk_bf16_f32 v227, v234, v235
	global_store_dwordx2 v224, v[226:227], s[56:57]
	s_add_u32 s56, s56, 0x4000
	s_addc_u32 s57, s57, 0
	s_waitcnt vmcnt(7) lgkmcnt(1)
	v_pk_fma_f32 v[236:237], v[178:179], s[36:37], v[236:237] op_sel_hi:[1,0,1]
	v_pk_fma_f32 v[238:239], v[180:181], s[36:37], v[238:239] op_sel_hi:[1,0,1]
	v_cvt_pk_bf16_f32 v244, v236, v237
	v_cvt_pk_bf16_f32 v245, v238, v239
	global_store_dwordx2 v224, v[244:245], s[56:57]
	s_add_u32 s56, s56, 0x4000
	s_addc_u32 s57, s57, 0
	s_waitcnt vmcnt(7) lgkmcnt(0)
	v_pk_fma_f32 v[240:241], v[182:183], s[36:37], v[240:241] op_sel_hi:[1,0,1]
	v_pk_fma_f32 v[242:243], v[184:185], s[36:37], v[242:243] op_sel_hi:[1,0,1]
	v_cvt_pk_bf16_f32 v226, v240, v241
	v_cvt_pk_bf16_f32 v227, v242, v243
	global_store_dwordx2 v224, v[226:227], s[56:57]
	s_branch .LBB0_780
